# k34: k20 + code placement: the six GEMM K-loop heads and the retention chunk-loop head padded to 64-byte boundaries
# speedup vs baseline: 1.0030x; 1.0008x over previous
; #define PG8_STAGE(bufoff, gbase, voff) do { _Pragma("unroll") for (int _i = 0; _i < 2; ++_i) \
;         __builtin_amdgcn_global_load_lds((const unsigned*)((const char*)(gbase) + (voff)[_i]), (LAS unsigned*)(lds + (bufoff) + ldsw + _i * 8192), 16, 0, 0); } while (0)
; template <class Epi>
; __device__ __forceinline__ void gemm_phase(LAS unsigned char* lds, const Gemm g, const Epi& E) {
;     ...
;     Unit cur, nxt; int ui = 0;
;     if (!S.next(0, cur)) return;
;     f32x4 acc[2][2][4][2];
; #pragma unroll
;     for (int a = 0; a < 2; ++a)
; #pragma unroll
;         for (int b = 0; b < 2; ++b)
; #pragma unroll
;             for (int m = 0; m < 4; ++m)
; #pragma unroll
;                 for (int n = 0; n < 2; ++n) acc[a][b][m][n] = (f32x4){0.f, 0.f, 0.f, 0.f};
;     bf16x8 At[4][2], B0[2][2], B1[2][2];
;     const char* cA = (const char*)g.A + (size_t)g.mapA.src(cur.pm) * tstepA + (size_t)cur.pn * g.a_pn_step;
;     const char* cB = (const char*)g.Bt + (size_t)g.mapB.src(cur.pn) * tstepB;
;     PG8_STAGE(PG8_SB(0, 0), cB, voffB); PG8_STAGE(PG8_SA(0, 0), cA, voffA); PG8_STAGE(PG8_SB(0, 1), cB + hstepB, voffB); PG8_STAGE(PG8_SA(0, 1), cA + hstepA, voffA);
.LBB0_295:
	s_lshl_b64 s[0:1], s[8:9], 17
	v_mov_b64_e32 v[2:3], s[76:77]
	s_add_u32 s5, s91, s0
	v_cmp_lt_i64_e32 vcc, s[12:13], v[2:3]
	s_addc_u32 s9, s25, s1
	s_and_b64 s[0:1], vcc, exec
	v_mov_b32_e32 v2, 0
	s_cselect_b32 s13, s9, s15
	s_cselect_b32 s12, s5, s14
	s_mov_b32 s5, 0
	s_mov_b64 s[28:29], -1
	s_mov_b64 s[58:59], 0
	v_mov_b32_e32 v3, v2
	v_mov_b64_e32 v[4:5], v[2:3]
	v_mov_b64_e32 v[6:7], v[2:3]
	v_mov_b64_e32 v[8:9], v[2:3]
	v_mov_b64_e32 v[10:11], v[2:3]
	v_mov_b64_e32 v[12:13], v[2:3]
	v_mov_b64_e32 v[14:15], v[2:3]
	v_mov_b64_e32 v[16:17], v[2:3]
	v_mov_b64_e32 v[18:19], v[2:3]
	v_mov_b64_e32 v[20:21], v[2:3]
	v_mov_b64_e32 v[22:23], v[2:3]
	v_mov_b64_e32 v[24:25], v[2:3]
	v_mov_b64_e32 v[26:27], v[2:3]
	v_mov_b64_e32 v[28:29], v[2:3]
	v_mov_b64_e32 v[30:31], v[2:3]
	v_mov_b64_e32 v[32:33], v[2:3]
	v_mov_b64_e32 v[34:35], v[2:3]
	v_mov_b64_e32 v[36:37], v[2:3]
	v_mov_b64_e32 v[38:39], v[2:3]
	v_mov_b64_e32 v[40:41], v[2:3]
	v_mov_b64_e32 v[42:43], v[2:3]
	v_mov_b64_e32 v[44:45], v[2:3]
	v_mov_b64_e32 v[46:47], v[2:3]
	v_mov_b64_e32 v[48:49], v[2:3]
	v_mov_b64_e32 v[50:51], v[2:3]
	v_mov_b64_e32 v[52:53], v[2:3]
	v_mov_b64_e32 v[54:55], v[2:3]
	v_mov_b64_e32 v[56:57], v[2:3]
	v_mov_b64_e32 v[58:59], v[2:3]
	v_mov_b64_e32 v[60:61], v[2:3]
	v_mov_b64_e32 v[62:63], v[2:3]
	v_mov_b64_e32 v[64:65], v[2:3]
	v_mov_b64_e32 v[66:67], v[2:3]
	v_mov_b64_e32 v[68:69], v[2:3]
	v_mov_b64_e32 v[70:71], v[2:3]
	v_mov_b64_e32 v[72:73], v[2:3]
	v_mov_b64_e32 v[74:75], v[2:3]
	v_mov_b64_e32 v[76:77], v[2:3]
	v_mov_b64_e32 v[78:79], v[2:3]
	v_mov_b64_e32 v[80:81], v[2:3]
	v_mov_b64_e32 v[82:83], v[2:3]
	v_mov_b64_e32 v[84:85], v[2:3]
	v_mov_b64_e32 v[86:87], v[2:3]
	v_mov_b64_e32 v[88:89], v[2:3]
	v_mov_b64_e32 v[90:91], v[2:3]
	v_mov_b64_e32 v[92:93], v[2:3]
	v_mov_b64_e32 v[94:95], v[2:3]
	v_mov_b64_e32 v[96:97], v[2:3]
	v_mov_b64_e32 v[98:99], v[2:3]
	v_mov_b64_e32 v[100:101], v[2:3]
	v_mov_b64_e32 v[102:103], v[2:3]
	v_mov_b64_e32 v[104:105], v[2:3]
	v_mov_b64_e32 v[106:107], v[2:3]
	v_mov_b64_e32 v[108:109], v[2:3]
	v_mov_b64_e32 v[110:111], v[2:3]
	v_mov_b64_e32 v[112:113], v[2:3]
	v_mov_b64_e32 v[114:115], v[2:3]
	v_mov_b64_e32 v[116:117], v[2:3]
	v_mov_b64_e32 v[118:119], v[2:3]
	v_mov_b64_e32 v[120:121], v[2:3]
	v_mov_b64_e32 v[122:123], v[2:3]
	v_mov_b64_e32 v[124:125], v[2:3]
	v_mov_b64_e32 v[126:127], v[2:3]
	v_mov_b64_e32 v[128:129], v[2:3]
	s_nop 0
	s_nop 0
	s_nop 0
	s_nop 0
	s_nop 0
	s_nop 0

; template <class Epi>
; __device__ __forceinline__ void gemm_phase(LAS unsigned char* lds, const Gemm g, const Epi& E) {
;     ...
;         const bool has_next = S.next(ui + 1, nxt);
;         const char* nA = has_next ? (const char*)g.A + (size_t)g.mapA.src(nxt.pm) * tstepA + (size_t)nxt.pn * g.a_pn_step : cA;
;         const char* nB = has_next ? (const char*)g.Bt + (size_t)g.mapB.src(nxt.pn) * tstepB : cB;
;     ...
; #pragma unroll
;         for (int a = 0; a < 2; ++a)
; #pragma unroll
;             for (int b = 0; b < 2; ++b)
; #pragma unroll
;                 for (int m = 0; m < 4; ++m)
; #pragma unroll
;                     for (int n = 0; n < 2; ++n) acc[a][b][m][n] = (f32x4){0.f, 0.f, 0.f, 0.f};
;         cur = nxt; cA = nA; cB = nB; ++ui;
.LBB0_330:
	s_ashr_i32 s15, s14, 31
	s_lshl_b64 s[52:53], s[14:15], 19
	s_add_u32 s15, s92, s52
	s_addc_u32 s52, s93, s53
	s_and_b64 s[4:5], s[4:5], exec
	s_cselect_b32 s59, s52, s65
	s_cselect_b32 s58, s15, s64
	s_add_u32 s4, s60, 0x40080
	s_addc_u32 s5, s61, 0
	s_add_u32 s15, s64, 0x100
	v_mov_b32_e32 v2, 0
	s_addc_u32 s52, s65, 0
	s_mov_b32 s53, -2
	v_mov_b32_e32 v3, v2
	v_mov_b64_e32 v[4:5], v[2:3]
	v_mov_b64_e32 v[6:7], v[2:3]
	v_mov_b64_e32 v[8:9], v[2:3]
	v_mov_b64_e32 v[10:11], v[2:3]
	v_mov_b64_e32 v[12:13], v[2:3]
	v_mov_b64_e32 v[14:15], v[2:3]
	v_mov_b64_e32 v[16:17], v[2:3]
	v_mov_b64_e32 v[18:19], v[2:3]
	v_mov_b64_e32 v[20:21], v[2:3]
	v_mov_b64_e32 v[22:23], v[2:3]
	v_mov_b64_e32 v[24:25], v[2:3]
	v_mov_b64_e32 v[26:27], v[2:3]
	v_mov_b64_e32 v[28:29], v[2:3]
	v_mov_b64_e32 v[30:31], v[2:3]
	v_mov_b64_e32 v[32:33], v[2:3]
	v_mov_b64_e32 v[34:35], v[2:3]
	v_mov_b64_e32 v[36:37], v[2:3]
	v_mov_b64_e32 v[38:39], v[2:3]
	v_mov_b64_e32 v[40:41], v[2:3]
	v_mov_b64_e32 v[42:43], v[2:3]
	v_mov_b64_e32 v[44:45], v[2:3]
	v_mov_b64_e32 v[46:47], v[2:3]
	v_mov_b64_e32 v[48:49], v[2:3]
	v_mov_b64_e32 v[50:51], v[2:3]
	v_mov_b64_e32 v[52:53], v[2:3]
	v_mov_b64_e32 v[54:55], v[2:3]
	v_mov_b64_e32 v[56:57], v[2:3]
	v_mov_b64_e32 v[58:59], v[2:3]
	v_mov_b64_e32 v[60:61], v[2:3]
	v_mov_b64_e32 v[62:63], v[2:3]
	v_mov_b64_e32 v[64:65], v[2:3]
	v_mov_b64_e32 v[66:67], v[2:3]
	v_mov_b64_e32 v[68:69], v[2:3]
	v_mov_b64_e32 v[70:71], v[2:3]
	v_mov_b64_e32 v[72:73], v[2:3]
	v_mov_b64_e32 v[78:79], v[2:3]
	v_mov_b64_e32 v[80:81], v[2:3]
	v_mov_b64_e32 v[90:91], v[2:3]
	v_mov_b64_e32 v[92:93], v[2:3]
	v_mov_b64_e32 v[98:99], v[2:3]
	v_mov_b64_e32 v[100:101], v[2:3]
	v_mov_b64_e32 v[102:103], v[2:3]
	v_mov_b64_e32 v[104:105], v[2:3]
	v_mov_b64_e32 v[114:115], v[2:3]
	v_mov_b64_e32 v[116:117], v[2:3]
	v_mov_b64_e32 v[118:119], v[2:3]
	v_mov_b64_e32 v[120:121], v[2:3]
	v_mov_b64_e32 v[122:123], v[2:3]
	v_mov_b64_e32 v[124:125], v[2:3]
	v_mov_b64_e32 v[126:127], v[2:3]
	v_mov_b64_e32 v[128:129], v[2:3]
	v_mov_b64_e32 v[138:139], v[2:3]
	v_mov_b64_e32 v[140:141], v[2:3]
	v_mov_b64_e32 v[142:143], v[2:3]
	v_mov_b64_e32 v[144:145], v[2:3]
	v_mov_b64_e32 v[146:147], v[2:3]
	v_mov_b64_e32 v[148:149], v[2:3]
	v_mov_b64_e32 v[150:151], v[2:3]
	v_mov_b64_e32 v[152:153], v[2:3]
	v_mov_b64_e32 v[162:163], v[2:3]
	v_mov_b64_e32 v[164:165], v[2:3]
	v_mov_b64_e32 v[166:167], v[2:3]
	v_mov_b64_e32 v[168:169], v[2:3]
	s_nop 0
	s_nop 0
	s_nop 0
	s_nop 0
	s_nop 0
	s_nop 0
	s_nop 0
	s_nop 0
	s_nop 0

; __device__ void ret_phase(const Params& p, unsigned char* ldsb, int lj, int half) {
;     ...
;             const float lg = -fabsf(p.ret_log_decay[(lj * 2 + dir) * 4 + h]);
;             const float l2g = lg * 1.4426950408889634f;
;             const float Gc = __builtin_amdgcn_exp2f(64.0f * l2g);
;             float ge[8];
; #pragma unroll
;             for (int e = 0; e < 8; ++e) ge[e] = __builtin_amdgcn_exp2f((dir == 0 ? -(float)e : (float)e) * l2g);
;             f32x4 S[16];
; #pragma unroll
;             for (int i = 0; i < 16; ++i) S[i] = (f32x4){0.f, 0.f, 0.f, 0.f};
;     ...
;                     const float qd = __builtin_amdgcn_exp2f((dir == 0 ? (float)(i + 1) : (float)(64 - i)) * l2g);
.LBB0_380:
	v_bfrev_b32_e32 v2, 1
	s_waitcnt vmcnt(10)
	v_mul_f32_e64 v191, |v1|, s95
	v_cndmask_b32_e64 v2, 0, v2, s[78:79]
	v_mul_f32_e32 v2, v2, v191
	v_exp_f32_e32 v192, v2
	v_cndmask_b32_e64 v2, v191, -v191, s[78:79]
	v_exp_f32_e32 v193, v2
	v_cndmask_b32_e64 v2, 2.0, -2.0, s[78:79]
	v_mul_f32_e32 v2, v2, v191
	v_exp_f32_e32 v194, v2
	v_mov_b32_e32 v2, 0x40400000
	v_mov_b32_e32 v3, 0xc0400000
	v_cndmask_b32_e64 v2, v2, v3, s[78:79]
	v_mul_f32_e32 v2, v2, v191
	v_exp_f32_e32 v195, v2
	v_cndmask_b32_e64 v2, 4.0, -4.0, s[78:79]
	v_mul_f32_e32 v2, v2, v191
	v_exp_f32_e32 v196, v2
	v_mov_b32_e32 v2, 0x40a00000
	v_cndmask_b32_e64 v2, v2, v220, s[78:79]
	v_mul_f32_e32 v1, 0x42800000, v191
	v_mul_f32_e32 v2, v2, v191
	v_exp_f32_e32 v197, v2
	v_cndmask_b32_e64 v2, v221, v222, s[78:79]
	v_exp_f32_e32 v172, v1
	v_cndmask_b32_e64 v1, v223, v224, s[78:79]
	v_mul_f32_e32 v2, v2, v191
	v_mul_f32_e32 v1, v1, v191
	v_exp_f32_e32 v198, v2
	v_exp_f32_e32 v199, v1
	v_add_u32_e32 v2, 1, v187
	v_sub_u32_e32 v3, 64, v187
	v_cndmask_b32_e64 v2, v3, v2, s[78:79]
	v_cvt_f32_i32_e32 v2, v2
	v_mul_f32_e32 v2, v191, v2
	v_exp_f32_e32 v252, v2
	v_add_u32_e32 v2, 17, v187
	v_sub_u32_e32 v3, 48, v187
	v_cndmask_b32_e64 v2, v3, v2, s[78:79]
	v_cvt_f32_i32_e32 v2, v2
	v_mul_f32_e32 v2, v191, v2
	v_exp_f32_e32 v253, v2
	v_add_u32_e32 v2, 33, v187
	v_sub_u32_e32 v3, 32, v187
	v_cndmask_b32_e64 v2, v3, v2, s[78:79]
	v_cvt_f32_i32_e32 v2, v2
	v_mul_f32_e32 v2, v191, v2
	v_exp_f32_e32 v209, v2
	v_add_u32_e32 v2, 49, v187
	v_sub_u32_e32 v3, 16, v187
	v_cndmask_b32_e64 v2, v3, v2, s[78:79]
	v_cvt_f32_i32_e32 v2, v2
	v_mul_f32_e32 v2, v191, v2
	v_exp_f32_e32 v225, v2
	v_mov_b32_e32 v2, v0
	v_mov_b32_e32 v3, v0
	v_mov_b32_e32 v1, v0
	v_mov_b64_e32 v[38:39], v[2:3]
	v_mov_b64_e32 v[62:63], v[2:3]
	v_mov_b64_e32 v[42:43], v[2:3]
	v_mov_b64_e32 v[66:67], v[2:3]
	v_mov_b64_e32 v[46:47], v[2:3]
	v_mov_b64_e32 v[70:71], v[2:3]
	v_mov_b64_e32 v[58:59], v[2:3]
	v_mov_b64_e32 v[74:75], v[2:3]
	v_mov_b64_e32 v[94:95], v[2:3]
	v_mov_b64_e32 v[78:79], v[2:3]
	v_mov_b64_e32 v[98:99], v[2:3]
	v_mov_b64_e32 v[82:83], v[2:3]
	v_mov_b64_e32 v[102:103], v[2:3]
	v_mov_b64_e32 v[86:87], v[2:3]
	v_mov_b64_e32 v[106:107], v[2:3]
	v_mov_b64_e32 v[90:91], v[2:3]
	s_xor_b64 s[60:61], s[58:59], -1
	v_mov_b32_e32 v174, v172
	v_mov_b32_e32 v175, v172
	s_mov_b32 s65, 0
	v_mov_b64_e32 v[36:37], v[0:1]
	v_mov_b64_e32 v[60:61], v[0:1]
	v_mov_b64_e32 v[40:41], v[0:1]
	v_mov_b64_e32 v[64:65], v[0:1]
	v_mov_b64_e32 v[44:45], v[0:1]
	v_mov_b64_e32 v[68:69], v[0:1]
	v_mov_b64_e32 v[56:57], v[0:1]
	v_mov_b64_e32 v[72:73], v[0:1]
	s_waitcnt vmcnt(0)
	v_mov_b64_e32 v[176:177], v[142:143]
	v_mov_b64_e32 v[180:181], v[140:141]
	v_mov_b64_e32 v[182:183], v[138:139]
	v_mov_b64_e32 v[184:185], v[136:137]
	v_mov_b64_e32 v[92:93], v[0:1]
	v_mov_b64_e32 v[76:77], v[0:1]
	v_mov_b64_e32 v[96:97], v[0:1]
	v_mov_b64_e32 v[80:81], v[0:1]
	v_mov_b64_e32 v[100:101], v[0:1]
	v_mov_b64_e32 v[84:85], v[0:1]
	v_mov_b64_e32 v[104:105], v[0:1]
	v_mov_b64_e32 v[88:89], v[0:1]
	s_mov_b32 s52, 0
	s_andn2_b64 vcc, exec, s[66:67]
	s_mov_b32 s53, s65
	s_cbranch_vccnz .LBB0_386
	s_branch .LBB0_382
	s_nop 0
	s_nop 0
	s_nop 0
	s_nop 0
	s_nop 0
	s_nop 0
	s_nop 0
	s_nop 0
	s_nop 0
	s_nop 0
	s_nop 0
	s_nop 0

; template <class Epi>
; __device__ __forceinline__ void gemm_phase(LAS unsigned char* lds, const Gemm g, const Epi& E) {
;     ...
; #pragma unroll
;         for (int a = 0; a < 2; ++a)
; #pragma unroll
;             for (int b = 0; b < 2; ++b)
; #pragma unroll
;                 for (int m = 0; m < 4; ++m)
; #pragma unroll
;                     for (int n = 0; n < 2; ++n) acc[a][b][m][n] = (f32x4){0.f, 0.f, 0.f, 0.f};
;         cur = nxt; cA = nA; cB = nB; ++ui;
.LBB0_474:
	s_ashr_i32 s9, s8, 31
	s_lshl_b64 s[28:29], s[8:9], 19
	v_readlane_b32 s9, v255, 28
	s_add_u32 s9, s9, s28
	v_readlane_b32 s28, v255, 29
	s_addc_u32 s28, s28, s29
	s_and_b64 s[4:5], s[4:5], exec
	s_cselect_b32 s5, s28, s17
	s_cselect_b32 s4, s9, s16
	s_add_u32 s14, s14, 0x40080
	s_addc_u32 s15, s15, 0
	s_add_u32 s9, s16, 0x100
	v_mov_b32_e32 v2, 0
	s_addc_u32 s53, s17, 0
	s_mov_b32 s65, -2
	v_mov_b32_e32 v3, v2
	v_mov_b32_e32 v4, v2
	v_mov_b32_e32 v5, v2
	v_mov_b32_e32 v6, v2
	v_mov_b32_e32 v7, v2
	v_mov_b32_e32 v8, v2
	v_mov_b32_e32 v9, v2
	v_mov_b32_e32 v18, v2
	v_mov_b32_e32 v19, v2
	v_mov_b32_e32 v20, v2
	v_mov_b32_e32 v21, v2
	v_mov_b32_e32 v22, v2
	v_mov_b32_e32 v23, v2
	s_waitcnt vmcnt(0)
	v_mov_b32_e32 v24, v2
	v_mov_b32_e32 v25, v2
	v_mov_b32_e32 v34, v2
	v_mov_b32_e32 v35, v2
	v_mov_b32_e32 v36, v2
	v_mov_b32_e32 v37, v2
	v_mov_b32_e32 v38, v2
	v_mov_b32_e32 v39, v2
	v_mov_b32_e32 v40, v2
	v_mov_b32_e32 v41, v2
	v_mov_b32_e32 v50, v2
	v_mov_b32_e32 v51, v2
	v_mov_b32_e32 v52, v2
	v_mov_b32_e32 v53, v2
	v_mov_b32_e32 v54, v2
	v_mov_b32_e32 v55, v2
	v_mov_b32_e32 v56, v2
	v_mov_b32_e32 v57, v2
	v_mov_b32_e32 v10, v2
	v_mov_b32_e32 v11, v2
	v_mov_b32_e32 v12, v2
	v_mov_b32_e32 v13, v2
	v_mov_b32_e32 v14, v2
	v_mov_b32_e32 v15, v2
	v_mov_b32_e32 v16, v2
	v_mov_b32_e32 v17, v2
	v_mov_b32_e32 v26, v2
	v_mov_b32_e32 v27, v2
	v_mov_b32_e32 v28, v2
	v_mov_b32_e32 v29, v2
	v_mov_b32_e32 v30, v2
	v_mov_b32_e32 v31, v2
	v_mov_b32_e32 v32, v2
	v_mov_b32_e32 v33, v2
	v_mov_b32_e32 v42, v2
	v_mov_b32_e32 v43, v2
	v_mov_b32_e32 v44, v2
	v_mov_b32_e32 v45, v2
	v_mov_b32_e32 v46, v2
	v_mov_b32_e32 v47, v2
	v_mov_b32_e32 v48, v2
	v_mov_b32_e32 v49, v2
	v_mov_b32_e32 v58, v2
	v_mov_b32_e32 v59, v2
	v_mov_b32_e32 v60, v2
	v_mov_b32_e32 v61, v2
	v_mov_b32_e32 v62, v2
	v_mov_b32_e32 v63, v2
	v_mov_b32_e32 v64, v2
	v_mov_b32_e32 v65, v2
	v_mov_b32_e32 v74, v2
	v_mov_b32_e32 v75, v2
	v_mov_b32_e32 v76, v2
	v_mov_b32_e32 v77, v2
	v_mov_b32_e32 v78, v2
	v_mov_b32_e32 v79, v2
	v_mov_b32_e32 v80, v2
	v_mov_b32_e32 v81, v2
	v_mov_b32_e32 v98, v2
	v_mov_b32_e32 v99, v2
	v_mov_b32_e32 v100, v2
	v_mov_b32_e32 v101, v2
	v_mov_b32_e32 v102, v2
	v_mov_b32_e32 v103, v2
	v_mov_b32_e32 v104, v2
	v_mov_b32_e32 v105, v2
	v_mov_b32_e32 v114, v2
	v_mov_b32_e32 v115, v2
	v_mov_b32_e32 v116, v2
	v_mov_b32_e32 v117, v2
	v_mov_b32_e32 v118, v2
	v_mov_b32_e32 v119, v2
	v_mov_b32_e32 v120, v2
	v_mov_b32_e32 v121, v2
	v_mov_b32_e32 v130, v2
	v_mov_b32_e32 v131, v2
	v_mov_b32_e32 v132, v2
	v_mov_b32_e32 v133, v2
	v_mov_b32_e32 v134, v2
	v_mov_b32_e32 v135, v2
	v_mov_b32_e32 v136, v2
	v_mov_b32_e32 v137, v2
	v_mov_b32_e32 v90, v2
	v_mov_b32_e32 v91, v2
	v_mov_b32_e32 v92, v2
	v_mov_b32_e32 v93, v2
	v_mov_b32_e32 v94, v2
	v_mov_b32_e32 v95, v2
	v_mov_b32_e32 v96, v2
	v_mov_b32_e32 v97, v2
	v_mov_b32_e32 v106, v2
	v_mov_b32_e32 v107, v2
	v_mov_b32_e32 v108, v2
	v_mov_b32_e32 v109, v2
	v_mov_b32_e32 v110, v2
	v_mov_b32_e32 v111, v2
	v_mov_b32_e32 v112, v2
	v_mov_b32_e32 v113, v2
	v_mov_b32_e32 v122, v2
	v_mov_b32_e32 v123, v2
	v_mov_b32_e32 v124, v2
	v_mov_b32_e32 v125, v2
	v_mov_b32_e32 v126, v2
	v_mov_b32_e32 v127, v2
	v_mov_b32_e32 v128, v2
	v_mov_b32_e32 v129, v2
	v_mov_b32_e32 v138, v2
	v_mov_b32_e32 v139, v2
	v_mov_b32_e32 v140, v2
	v_mov_b32_e32 v141, v2
	v_mov_b32_e32 v142, v2
	v_mov_b32_e32 v143, v2
	v_mov_b32_e32 v144, v2
	v_mov_b32_e32 v145, v2
	s_nop 0
	s_nop 0
	s_nop 0

; template <class Epi>
; __device__ __forceinline__ void gemm_phase(LAS unsigned char* lds, const Gemm g, const Epi& E) {
;     ...
; #pragma unroll
;         for (int a = 0; a < 2; ++a)
; #pragma unroll
;             for (int b = 0; b < 2; ++b)
; #pragma unroll
;                 for (int m = 0; m < 4; ++m)
; #pragma unroll
;                     for (int n = 0; n < 2; ++n) acc[a][b][m][n] = (f32x4){0.f, 0.f, 0.f, 0.f};
;         cur = nxt; cA = nA; cB = nB; ++ui;
.LBB0_494:
	s_ashr_i32 s7, s6, 31
	s_lshl_b64 s[16:17], s[6:7], 20
	s_add_u32 s7, s18, s16
	s_addc_u32 s16, s24, s17
	s_and_b64 s[4:5], s[4:5], exec
	s_cselect_b32 s5, s16, s15
	s_cselect_b32 s4, s7, s14
	s_add_u32 s12, s12, 0x80080
	s_addc_u32 s13, s13, 0
	s_add_u32 s7, s14, 0x100
	v_mov_b32_e32 v2, 0
	s_addc_u32 s64, s15, 0
	s_mov_b32 s65, -2
	v_mov_b32_e32 v3, v2
	v_mov_b64_e32 v[4:5], v[2:3]
	v_mov_b64_e32 v[6:7], v[2:3]
	v_mov_b64_e32 v[8:9], v[2:3]
	v_mov_b64_e32 v[10:11], v[2:3]
	v_mov_b64_e32 v[12:13], v[2:3]
	v_mov_b64_e32 v[14:15], v[2:3]
	v_mov_b64_e32 v[16:17], v[2:3]
	v_mov_b64_e32 v[18:19], v[2:3]
	v_mov_b64_e32 v[20:21], v[2:3]
	v_mov_b64_e32 v[22:23], v[2:3]
	v_mov_b64_e32 v[24:25], v[2:3]
	v_mov_b64_e32 v[26:27], v[2:3]
	v_mov_b64_e32 v[28:29], v[2:3]
	v_mov_b64_e32 v[30:31], v[2:3]
	v_mov_b64_e32 v[32:33], v[2:3]
	v_mov_b64_e32 v[34:35], v[2:3]
	v_mov_b64_e32 v[36:37], v[2:3]
	v_mov_b64_e32 v[38:39], v[2:3]
	v_mov_b64_e32 v[40:41], v[2:3]
	v_mov_b64_e32 v[42:43], v[2:3]
	v_mov_b64_e32 v[44:45], v[2:3]
	v_mov_b64_e32 v[46:47], v[2:3]
	v_mov_b64_e32 v[48:49], v[2:3]
	v_mov_b64_e32 v[50:51], v[2:3]
	v_mov_b64_e32 v[52:53], v[2:3]
	v_mov_b64_e32 v[54:55], v[2:3]
	v_mov_b64_e32 v[56:57], v[2:3]
	v_mov_b64_e32 v[58:59], v[2:3]
	v_mov_b64_e32 v[60:61], v[2:3]
	v_mov_b64_e32 v[62:63], v[2:3]
	v_mov_b64_e32 v[64:65], v[2:3]
	v_mov_b64_e32 v[66:67], v[2:3]
	v_mov_b64_e32 v[68:69], v[2:3]
	v_mov_b64_e32 v[70:71], v[2:3]
	v_mov_b64_e32 v[72:73], v[2:3]
	v_mov_b64_e32 v[74:75], v[2:3]
	v_mov_b64_e32 v[76:77], v[2:3]
	v_mov_b64_e32 v[78:79], v[2:3]
	v_mov_b64_e32 v[80:81], v[2:3]
	v_mov_b64_e32 v[82:83], v[2:3]
	v_mov_b64_e32 v[84:85], v[2:3]
	v_mov_b64_e32 v[86:87], v[2:3]
	v_mov_b64_e32 v[88:89], v[2:3]
	v_mov_b64_e32 v[90:91], v[2:3]
	v_mov_b64_e32 v[92:93], v[2:3]
	v_mov_b64_e32 v[94:95], v[2:3]
	v_mov_b64_e32 v[96:97], v[2:3]
	v_mov_b64_e32 v[98:99], v[2:3]
	v_mov_b64_e32 v[100:101], v[2:3]
	v_mov_b64_e32 v[102:103], v[2:3]
	v_mov_b64_e32 v[104:105], v[2:3]
	v_mov_b64_e32 v[106:107], v[2:3]
	v_mov_b64_e32 v[108:109], v[2:3]
	v_mov_b64_e32 v[110:111], v[2:3]
	v_mov_b64_e32 v[112:113], v[2:3]
	v_mov_b64_e32 v[114:115], v[2:3]
	v_mov_b64_e32 v[116:117], v[2:3]
	v_mov_b64_e32 v[118:119], v[2:3]
	v_mov_b64_e32 v[120:121], v[2:3]
	v_mov_b64_e32 v[122:123], v[2:3]
	v_mov_b64_e32 v[124:125], v[2:3]
	v_mov_b64_e32 v[126:127], v[2:3]
	v_mov_b64_e32 v[128:129], v[2:3]
	s_nop 0
	s_nop 0
	s_nop 0
	s_nop 0
	s_nop 0
	s_nop 0
	s_nop 0
	s_nop 0
	s_nop 0

; template <class Epi>
; __device__ __forceinline__ void gemm_phase(LAS unsigned char* lds, const Gemm g, const Epi& E) {
;     ...
; #pragma unroll
;         for (int a = 0; a < 2; ++a)
; #pragma unroll
;             for (int b = 0; b < 2; ++b)
; #pragma unroll
;                 for (int m = 0; m < 4; ++m)
; #pragma unroll
;                     for (int n = 0; n < 2; ++n) acc[a][b][m][n] = (f32x4){0.f, 0.f, 0.f, 0.f};
;         cur = nxt; cA = nA; cB = nB; ++ui;
.LBB0_524:
	s_ashr_i32 s7, s6, 31
	s_lshl_b64 s[16:17], s[6:7], 19
	s_add_u32 s7, s18, s16
	s_addc_u32 s16, s24, s17
	s_and_b64 s[4:5], s[4:5], exec
	s_cselect_b32 s5, s16, s15
	s_cselect_b32 s4, s7, s14
	s_add_u32 s12, s12, 0x40080
	s_addc_u32 s13, s13, 0
	s_add_u32 s7, s14, 0x100
	v_mov_b32_e32 v2, 0
	s_addc_u32 s65, s15, 0
	s_mov_b32 s66, -2
	v_mov_b32_e32 v3, v2
	v_mov_b64_e32 v[4:5], v[2:3]
	v_mov_b64_e32 v[6:7], v[2:3]
	v_mov_b64_e32 v[8:9], v[2:3]
	v_mov_b64_e32 v[10:11], v[2:3]
	v_mov_b64_e32 v[12:13], v[2:3]
	v_mov_b64_e32 v[14:15], v[2:3]
	v_mov_b64_e32 v[16:17], v[2:3]
	v_mov_b64_e32 v[18:19], v[2:3]
	v_mov_b64_e32 v[20:21], v[2:3]
	v_mov_b64_e32 v[22:23], v[2:3]
	v_mov_b64_e32 v[24:25], v[2:3]
	v_mov_b64_e32 v[26:27], v[2:3]
	v_mov_b64_e32 v[28:29], v[2:3]
	v_mov_b64_e32 v[30:31], v[2:3]
	v_mov_b64_e32 v[32:33], v[2:3]
	v_mov_b64_e32 v[34:35], v[2:3]
	v_mov_b64_e32 v[36:37], v[2:3]
	v_mov_b64_e32 v[38:39], v[2:3]
	v_mov_b64_e32 v[40:41], v[2:3]
	v_mov_b64_e32 v[42:43], v[2:3]
	v_mov_b64_e32 v[44:45], v[2:3]
	v_mov_b64_e32 v[46:47], v[2:3]
	v_mov_b64_e32 v[48:49], v[2:3]
	v_mov_b64_e32 v[50:51], v[2:3]
	v_mov_b64_e32 v[52:53], v[2:3]
	v_mov_b64_e32 v[54:55], v[2:3]
	v_mov_b64_e32 v[56:57], v[2:3]
	v_mov_b64_e32 v[58:59], v[2:3]
	v_mov_b64_e32 v[60:61], v[2:3]
	v_mov_b64_e32 v[62:63], v[2:3]
	v_mov_b64_e32 v[64:65], v[2:3]
	v_mov_b64_e32 v[66:67], v[2:3]
	v_mov_b64_e32 v[68:69], v[2:3]
	v_mov_b64_e32 v[70:71], v[2:3]
	v_mov_b64_e32 v[72:73], v[2:3]
	v_mov_b64_e32 v[74:75], v[2:3]
	v_mov_b64_e32 v[76:77], v[2:3]
	v_mov_b64_e32 v[78:79], v[2:3]
	v_mov_b64_e32 v[80:81], v[2:3]
	v_mov_b64_e32 v[82:83], v[2:3]
	v_mov_b64_e32 v[84:85], v[2:3]
	v_mov_b64_e32 v[86:87], v[2:3]
	v_mov_b64_e32 v[88:89], v[2:3]
	v_mov_b64_e32 v[90:91], v[2:3]
	v_mov_b64_e32 v[92:93], v[2:3]
	v_mov_b64_e32 v[94:95], v[2:3]
	v_mov_b64_e32 v[96:97], v[2:3]
	v_mov_b64_e32 v[98:99], v[2:3]
	v_mov_b64_e32 v[100:101], v[2:3]
	v_mov_b64_e32 v[102:103], v[2:3]
	v_mov_b64_e32 v[104:105], v[2:3]
	v_mov_b64_e32 v[106:107], v[2:3]
	v_mov_b64_e32 v[108:109], v[2:3]
	v_mov_b64_e32 v[110:111], v[2:3]
	v_mov_b64_e32 v[112:113], v[2:3]
	v_mov_b64_e32 v[114:115], v[2:3]
	v_mov_b64_e32 v[116:117], v[2:3]
	v_mov_b64_e32 v[118:119], v[2:3]
	v_mov_b64_e32 v[120:121], v[2:3]
	v_mov_b64_e32 v[122:123], v[2:3]
	v_mov_b64_e32 v[124:125], v[2:3]
	v_mov_b64_e32 v[126:127], v[2:3]
	v_mov_b64_e32 v[128:129], v[2:3]
	s_nop 0
	s_nop 0
	s_nop 0
	s_nop 0
	s_nop 0
	s_nop 0
	s_nop 0
	s_nop 0
	s_nop 0

; template <class Epi>
; __device__ __forceinline__ void gemm_phase(LAS unsigned char* lds, const Gemm g, const Epi& E) {
;     ...
; #pragma unroll
;         for (int a = 0; a < 2; ++a)
; #pragma unroll
;             for (int b = 0; b < 2; ++b)
; #pragma unroll
;                 for (int m = 0; m < 4; ++m)
; #pragma unroll
;                     for (int n = 0; n < 2; ++n) acc[a][b][m][n] = (f32x4){0.f, 0.f, 0.f, 0.f};
;         cur = nxt; cA = nA; cB = nB; ++ui;
.LBB0_546:
	s_add_u32 s65, s10, 0x100
	v_mov_b32_e32 v2, 0
	s_addc_u32 s66, s11, 0
	s_mov_b32 s67, -2
	v_mov_b32_e32 v3, v2
	v_mov_b64_e32 v[4:5], v[2:3]
	v_mov_b64_e32 v[6:7], v[2:3]
	v_mov_b64_e32 v[8:9], v[2:3]
	v_mov_b64_e32 v[10:11], v[2:3]
	v_mov_b64_e32 v[12:13], v[2:3]
	v_mov_b64_e32 v[14:15], v[2:3]
	v_mov_b64_e32 v[16:17], v[2:3]
	v_mov_b64_e32 v[18:19], v[2:3]
	v_mov_b64_e32 v[20:21], v[2:3]
	v_mov_b64_e32 v[22:23], v[2:3]
	v_mov_b64_e32 v[24:25], v[2:3]
	v_mov_b64_e32 v[26:27], v[2:3]
	v_mov_b64_e32 v[28:29], v[2:3]
	v_mov_b64_e32 v[30:31], v[2:3]
	v_mov_b64_e32 v[32:33], v[2:3]
	v_mov_b64_e32 v[34:35], v[2:3]
	v_mov_b64_e32 v[36:37], v[2:3]
	v_mov_b64_e32 v[38:39], v[2:3]
	v_mov_b64_e32 v[40:41], v[2:3]
	v_mov_b64_e32 v[42:43], v[2:3]
	v_mov_b64_e32 v[44:45], v[2:3]
	v_mov_b64_e32 v[46:47], v[2:3]
	v_mov_b64_e32 v[48:49], v[2:3]
	v_mov_b64_e32 v[50:51], v[2:3]
	v_mov_b64_e32 v[52:53], v[2:3]
	v_mov_b64_e32 v[54:55], v[2:3]
	v_mov_b64_e32 v[56:57], v[2:3]
	v_mov_b64_e32 v[58:59], v[2:3]
	v_mov_b64_e32 v[60:61], v[2:3]
	v_mov_b64_e32 v[62:63], v[2:3]
	v_mov_b64_e32 v[64:65], v[2:3]
	v_mov_b64_e32 v[66:67], v[2:3]
	v_mov_b64_e32 v[68:69], v[2:3]
	v_mov_b64_e32 v[70:71], v[2:3]
	v_mov_b64_e32 v[72:73], v[2:3]
	v_mov_b64_e32 v[74:75], v[2:3]
	v_mov_b64_e32 v[76:77], v[2:3]
	v_mov_b64_e32 v[78:79], v[2:3]
	v_mov_b64_e32 v[80:81], v[2:3]
	v_mov_b64_e32 v[82:83], v[2:3]
	v_mov_b64_e32 v[84:85], v[2:3]
	v_mov_b64_e32 v[86:87], v[2:3]
	v_mov_b64_e32 v[88:89], v[2:3]
	v_mov_b64_e32 v[90:91], v[2:3]
	v_mov_b64_e32 v[92:93], v[2:3]
	v_mov_b64_e32 v[94:95], v[2:3]
	v_mov_b64_e32 v[96:97], v[2:3]
	v_mov_b64_e32 v[98:99], v[2:3]
	v_mov_b64_e32 v[100:101], v[2:3]
	v_mov_b64_e32 v[102:103], v[2:3]
	v_mov_b64_e32 v[104:105], v[2:3]
	v_mov_b64_e32 v[106:107], v[2:3]
	v_mov_b64_e32 v[108:109], v[2:3]
	v_mov_b64_e32 v[110:111], v[2:3]
	v_mov_b64_e32 v[112:113], v[2:3]
	v_mov_b64_e32 v[114:115], v[2:3]
	v_mov_b64_e32 v[116:117], v[2:3]
	v_mov_b64_e32 v[118:119], v[2:3]
	v_mov_b64_e32 v[120:121], v[2:3]
	v_mov_b64_e32 v[122:123], v[2:3]
	v_mov_b64_e32 v[124:125], v[2:3]
	v_mov_b64_e32 v[126:127], v[2:3]
	v_mov_b64_e32 v[128:129], v[2:3]
	s_nop 0
	s_nop 0
